# diff attention loop: first eight transposed V reads of each PV block issued before the convert/permute/address block (as soon as their destination registers are free)
# speedup vs baseline: 1.0092x; 1.0092x over previous
; template <int D0> __device__ __forceinline__ void pv_one(f32x16& od, int vb, bf16x8 pa0, bf16x8 pa1, bf16x8 pa2, bf16x8 pa3) {
;     const s16x4 l0 = tr_read<v_rd_off(D0, 0, 0)>(vb), h0 = tr_read<v_rd_off(D0, 0, 1)>(vb), l1 = tr_read<v_rd_off(D0, 1, 0)>(vb), h1 = tr_read<v_rd_off(D0, 1, 1)>(vb);
;     const s16x4 l2 = tr_read<v_rd_off(D0, 2, 0)>(vb), h2 = tr_read<v_rd_off(D0, 2, 1)>(vb), l3 = tr_read<v_rd_off(D0, 3, 0)>(vb), h3 = tr_read<v_rd_off(D0, 3, 1)>(vb);
;     asm volatile("s_waitcnt lgkmcnt(0)" ::: "memory"); SBAR();
;     ...
;     od = __builtin_amdgcn_mfma_f32_32x32x16_bf16(pa0, PK(l0, h0), od, 0, 0, 0);
;     od = __builtin_amdgcn_mfma_f32_32x32x16_bf16(pa1, PK(l1, h1), od, 0, 0, 0);
;     od = __builtin_amdgcn_mfma_f32_32x32x16_bf16(pa2, PK(l2, h2), od, 0, 0, 0);
;     od = __builtin_amdgcn_mfma_f32_32x32x16_bf16(pa3, PK(l3, h3), od, 0, 0, 0);
;     ...
; }
; __device__ __forceinline__ void pv_d0(f32x16* o, int vb, bf16x8 pa0, bf16x8 pa1, bf16x8 pa2, bf16x8 pa3) {
;     pv_one<0>(o[0], vb, pa0, pa1, pa2, pa3); pv_one<1>(o[1], vb, pa0, pa1, pa2, pa3); pv_one<2>(o[2], vb, pa0, pa1, pa2, pa3); pv_one<3>(o[3], vb, pa0, pa1, pa2, pa3);
; }
; __device__ __forceinline__ void partialSM(f32x16& p0, f32x16& p1, float& m_reg, float& mn, float& alpha, const float C, const float thr) {
;     float pmax = p0[0];
; #pragma unroll
;     for (int r = 1; r < 16; ++r) pmax = fmaxf(pmax, p0[r]);
; #pragma unroll
;     for (int r = 0; r < 16; ++r) pmax = fmaxf(pmax, p1[r]);
;     { auto rr = __builtin_amdgcn_permlane32_swap(__float_as_uint(pmax), __float_as_uint(pmax), false, false);
;       pmax = fmaxf(__uint_as_float(rr[0]), __uint_as_float(rr[1])); }
;     if (__builtin_expect(__all(pmax - m_reg <= thr), 1)) { mn = m_reg; alpha = 1.f; }
;     else { mn = fmaxf(m_reg, pmax); alpha = __builtin_amdgcn_exp2f((m_reg - mn) * C); m_reg = mn; }
;     const float mnC = -mn * C;
; #pragma unroll
;     for (int r = 0; r < 16; ++r) p0[r] = fmaf(p0[r], C, mnC);
; #pragma unroll
;     for (int r = 0; r < 16; ++r) p1[r] = fmaf(p1[r], C, mnC);
; #pragma unroll
;     for (int r = 0; r < 16; ++r) p0[r] = __builtin_amdgcn_exp2f(p0[r]);
; }
; __device__ __forceinline__ void finishSM(f32x16& p0, f32x16& p1, float alpha, float& l_reg, bf16x8& pa0, bf16x8& pa1, bf16x8& pa2, bf16x8& pa3) {
; #pragma unroll
;     for (int r = 0; r < 16; ++r) p1[r] = __builtin_amdgcn_exp2f(p1[r]);
;     float ps = 0;
.LBB0_171:
	s_add_i32 s37, s52, -3
	ds_read_b128 v[64:67], v186 offset:40960
	ds_read_b128 v[68:71], v186 offset:45056
	v_exp_f32_e32 v143, v138
	v_add_f32_e32 v138, 0, v217
	v_add_f32_e32 v138, v219, v138
	s_waitcnt lgkmcnt(1)
	v_mfma_f32_32x32x16_bf16 v[80:95], v[64:67], v[110:113], 0
	v_add_f32_e32 v138, v208, v138
	v_add_f32_e32 v138, v218, v138
	v_add_f32_e32 v138, v153, v138
	ds_read_b128 v[204:207], v188 offset:40960
	ds_read_b128 v[220:223], v188 offset:45056
	v_add_f32_e32 v138, v216, v138
	v_add_f32_e32 v138, v152, v138
	v_add_f32_e32 v138, v202, v138
	s_waitcnt lgkmcnt(2)
	v_mfma_f32_32x32x16_bf16 v[64:79], v[68:71], v[110:113], 0
	v_add_f32_e32 v138, v149, v138
	v_add_f32_e32 v138, v151, v138
	v_add_f32_e32 v138, v147, v138
	v_add_f32_e32 v138, v150, v138
	v_add_f32_e32 v138, v145, v138
	v_exp_f32_e32 v191, v139
	v_add_f32_e32 v138, v148, v138
	s_waitcnt lgkmcnt(1)
	v_mfma_f32_32x32x16_bf16 v[80:95], v[204:207], v[106:109], v[80:95]
	v_exp_f32_e32 v136, v136
	v_add_f32_e32 v138, v144, v138
	v_exp_f32_e32 v137, v137
	v_add_f32_e32 v138, v146, v138
	v_exp_f32_e32 v130, v130
	v_add_f32_e32 v138, v143, v138
	v_exp_f32_e32 v131, v131
	s_waitcnt lgkmcnt(0)
	v_mfma_f32_32x32x16_bf16 v[64:79], v[220:223], v[106:109], v[64:79]
	ds_read_b128 v[204:207], v190 offset:40960
	ds_read_b128 v[220:223], v190 offset:45056
	v_add_f32_e32 v138, v191, v138
	v_exp_f32_e32 v128, v128
	v_add_f32_e32 v138, v136, v138
	v_exp_f32_e32 v129, v129
	v_add_f32_e32 v138, v137, v138
	v_exp_f32_e32 v126, v126
	s_waitcnt lgkmcnt(1)
	v_mfma_f32_32x32x16_bf16 v[80:95], v[204:207], v[102:105], v[80:95]
	v_add_f32_e32 v138, v130, v138
	v_exp_f32_e32 v127, v127
	v_add_f32_e32 v138, v131, v138
	v_exp_f32_e32 v200, v140
	v_add_f32_e32 v138, v128, v138
	v_exp_f32_e32 v210, v141
	v_add_f32_e32 v138, v129, v138
	s_waitcnt lgkmcnt(0)
	v_mfma_f32_32x32x16_bf16 v[64:79], v[220:223], v[102:105], v[64:79]
	ds_read_b128 v[204:207], v192 offset:40960
	ds_read_b128 v[220:223], v192 offset:45056
	v_exp_f32_e32 v134, v134
	v_add_f32_e32 v138, v126, v138
	v_exp_f32_e32 v135, v135
	v_add_f32_e32 v138, v127, v138
	v_exp_f32_e32 v132, v132
	v_add_f32_e32 v138, v200, v138
	s_waitcnt lgkmcnt(1)
	v_mfma_f32_32x32x16_bf16 v[80:95], v[204:207], v[98:101], v[80:95]
	v_exp_f32_e32 v133, v133
	v_add_f32_e32 v138, v210, v138
	v_add_f32_e32 v138, v134, v138
	v_add_f32_e32 v138, v135, v138
	v_add_f32_e32 v138, v132, v138
	v_add_f32_e32 v196, v133, v138
	v_mov_b32_e32 v198, v196
	s_waitcnt lgkmcnt(0)
	v_mfma_f32_32x32x16_bf16 v[64:79], v[220:223], v[98:101], v[64:79]
	ds_read_b64_tr_b16 v[220:221], v180 offset:0x1000
	ds_read_b64_tr_b16 v[222:223], v180 offset:0x1800
	ds_read_b64_tr_b16 v[224:225], v180 offset:0x2000
	ds_read_b64_tr_b16 v[226:227], v180 offset:0x2800
	ds_read_b64_tr_b16 v[228:229], v180 offset:0x3000
	ds_read_b64_tr_b16 v[230:231], v180 offset:0x3800
	v_cvt_pk_bf16_f32 v138, v217, v219
	v_cvt_pk_bf16_f32 v139, v208, v218
	v_cvt_pk_bf16_f32 v140, v153, v216
	ds_read_b64_tr_b16 v[216:217], v180 offset:0
	ds_read_b64_tr_b16 v[218:219], v180 offset:0x800
	v_permlane32_swap_b32_e32 v196, v198
	v_cvt_pk_bf16_f32 v141, v152, v202
	v_permlane32_swap_b32_e32 v138, v140
	v_cvt_pk_bf16_f32 v204, v149, v151
	v_cvt_pk_bf16_f32 v205, v147, v150
	v_cvt_pk_bf16_f32 v206, v145, v148
	v_cvt_pk_bf16_f32 v207, v144, v146
	v_cvt_pk_bf16_f32 v144, v143, v191
	v_cvt_pk_bf16_f32 v145, v136, v137
	v_cvt_pk_bf16_f32 v146, v130, v131
	v_cvt_pk_bf16_f32 v147, v128, v129
	v_cvt_pk_bf16_f32 v148, v126, v127
	v_cvt_pk_bf16_f32 v149, v200, v210
	v_cvt_pk_bf16_f32 v150, v134, v135
	v_cvt_pk_bf16_f32 v151, v132, v133
	v_permlane32_swap_b32_e32 v139, v141
	v_permlane32_swap_b32_e32 v204, v206
	v_permlane32_swap_b32_e32 v205, v207
	v_permlane32_swap_b32_e32 v144, v146
	v_permlane32_swap_b32_e32 v145, v147
	v_permlane32_swap_b32_e32 v148, v150
	v_permlane32_swap_b32_e32 v149, v151
	s_cmp_lt_u32 s37, 30
	s_cselect_b32 s14, 0, 0xffffffe0
	s_cselect_b32 s15, s18, s86
	s_add_i32 s14, s14, s52
	s_lshl_b32 s14, s14, 6
	s_add_i32 s14, s14, s15
	s_sub_i32 s14, s14, 64
	s_ashr_i32 s15, s14, 31
	v_lshl_add_u64 v[126:127], s[14:15], 0, v[164:165]
	v_lshl_add_u64 v[130:131], v[168:169], 0, s[14:15]
	v_mad_u64_u32 v[128:129], s[38:39], v126, s9, v[170:171]
	v_mad_u64_u32 v[132:133], s[38:39], v130, s9, v[170:171]
	v_mad_i32_i24 v129, v127, s9, v129
	v_mad_i32_i24 v133, v131, s9, v133
	v_mad_i64_i32 v[134:135], s[14:15], s14, v195, v[166:167]
	global_load_dwordx4 v[126:129], v[128:129], off
	s_nop 0
	global_load_dwordx4 v[130:133], v[132:133], off
	s_nop 0
	global_load_dwordx4 v[134:137], v[134:135], off
	s_waitcnt lgkmcnt(0)
	s_nop 0
	v_mfma_f32_32x32x16_bf16 v[48:63], v[138:141], v[216:219], v[48:63]
	ds_read_b64_tr_b16 v[216:217], v180 offset:0x200
	ds_read_b64_tr_b16 v[218:219], v180 offset:0xa00
	v_max_f32_e32 v238, v81, v81
	v_max_f32_e32 v239, v80, v80
	v_max_f32_e32 v238, v239, v238
	v_max3_f32 v238, v238, v82, v83
	v_max3_f32 v238, v238, v84, v85
	v_max3_f32 v238, v238, v86, v87
	v_mfma_f32_32x32x16_bf16 v[48:63], v[204:207], v[220:223], v[48:63]
	ds_read_b64_tr_b16 v[220:221], v180 offset:0x1200
	ds_read_b64_tr_b16 v[222:223], v180 offset:0x1a00
	v_max3_f32 v238, v238, v88, v89
	v_max3_f32 v238, v238, v90, v91
	v_max3_f32 v238, v238, v92, v93
	v_max3_f32 v238, v238, v94, v95
	v_max3_f32 v238, v238, v64, v65
	v_max3_f32 v238, v238, v66, v67
	v_mfma_f32_32x32x16_bf16 v[48:63], v[144:147], v[224:227], v[48:63]
	ds_read_b64_tr_b16 v[224:225], v180 offset:0x2200
	ds_read_b64_tr_b16 v[226:227], v180 offset:0x2a00
	v_max3_f32 v238, v238, v68, v69
	v_max3_f32 v238, v238, v70, v71
	v_max3_f32 v238, v238, v72, v73
	v_max3_f32 v238, v238, v74, v75
	v_max3_f32 v238, v238, v76, v77
	v_max3_f32 v238, v238, v78, v79
	v_mfma_f32_32x32x16_bf16 v[48:63], v[148:151], v[228:231], v[48:63]
	ds_read_b64_tr_b16 v[228:229], v180 offset:0x3200
	ds_read_b64_tr_b16 v[230:231], v180 offset:0x3a00
	v_mov_b32_e32 v239, v238
	s_nop 1
	v_permlane32_swap_b32_e32 v238, v239
	v_max_f32_e32 v239, v239, v239
	v_max_f32_e32 v238, v238, v238
	v_max_f32_e32 v238, v238, v239
	s_waitcnt lgkmcnt(0)
; #define SBAR() __builtin_amdgcn_sched_barrier(0)
; template <int OFF> __device__ __forceinline__ s16x4 tr_read(int vb) { s16x4 r; asm volatile("ds_read_b64_tr_b16 %0, %1 offset:%2" : "=&v"(r) : "v"(vb), "i"(OFF) : "memory"); return r; }
; template <int D0> __device__ __forceinline__ void pv_one(f32x16& od, int vb, bf16x8 pa0, bf16x8 pa1, bf16x8 pa2, bf16x8 pa3) {
;     const s16x4 l0 = tr_read<v_rd_off(D0, 0, 0)>(vb), h0 = tr_read<v_rd_off(D0, 0, 1)>(vb), l1 = tr_read<v_rd_off(D0, 1, 0)>(vb), h1 = tr_read<v_rd_off(D0, 1, 1)>(vb);
;     const s16x4 l2 = tr_read<v_rd_off(D0, 2, 0)>(vb), h2 = tr_read<v_rd_off(D0, 2, 1)>(vb), l3 = tr_read<v_rd_off(D0, 3, 0)>(vb), h3 = tr_read<v_rd_off(D0, 3, 1)>(vb);
;     asm volatile("s_waitcnt lgkmcnt(0)" ::: "memory"); SBAR();
;     ...
;     od = __builtin_amdgcn_mfma_f32_32x32x16_bf16(pa0, PK(l0, h0), od, 0, 0, 0);
;     od = __builtin_amdgcn_mfma_f32_32x32x16_bf16(pa1, PK(l1, h1), od, 0, 0, 0);
;     od = __builtin_amdgcn_mfma_f32_32x32x16_bf16(pa2, PK(l2, h2), od, 0, 0, 0);
;     od = __builtin_amdgcn_mfma_f32_32x32x16_bf16(pa3, PK(l3, h3), od, 0, 0, 0);
;     ...
; }
; __device__ __forceinline__ void pv_d0(f32x16* o, int vb, bf16x8 pa0, bf16x8 pa1, bf16x8 pa2, bf16x8 pa3) {
;     pv_one<0>(o[0], vb, pa0, pa1, pa2, pa3); pv_one<1>(o[1], vb, pa0, pa1, pa2, pa3); pv_one<2>(o[2], vb, pa0, pa1, pa2, pa3); pv_one<3>(o[3], vb, pa0, pa1, pa2, pa3);
; }
; __device__ __forceinline__ void partialSM(f32x16& p0, f32x16& p1, float& m_reg, float& mn, float& alpha, const float C, const float thr) {
;     float pmax = p0[0];
; #pragma unroll
;     for (int r = 1; r < 16; ++r) pmax = fmaxf(pmax, p0[r]);
; #pragma unroll
;     for (int r = 0; r < 16; ++r) pmax = fmaxf(pmax, p1[r]);
;     { auto rr = __builtin_amdgcn_permlane32_swap(__float_as_uint(pmax), __float_as_uint(pmax), false, false);
;       pmax = fmaxf(__uint_as_float(rr[0]), __uint_as_float(rr[1])); }
;     if (__builtin_expect(__all(pmax - m_reg <= thr), 1)) { mn = m_reg; alpha = 1.f; }
;     else { mn = fmaxf(m_reg, pmax); alpha = __builtin_amdgcn_exp2f((m_reg - mn) * C); m_reg = mn; }
;     const float mnC = -mn * C;
; #pragma unroll
;     for (int r = 0; r < 16; ++r) p0[r] = fmaf(p0[r], C, mnC);
; #pragma unroll
;     for (int r = 0; r < 16; ++r) p1[r] = fmaf(p1[r], C, mnC);
; #pragma unroll
;     for (int r = 0; r < 16; ++r) p0[r] = __builtin_amdgcn_exp2f(p0[r]);
; }
	v_mfma_f32_32x32x16_bf16 v[32:47], v[138:141], v[216:219], v[32:47]
	ds_read_b64_tr_b16 v[216:217], v180 offset:0x400
	ds_read_b64_tr_b16 v[218:219], v180 offset:0xc00
	v_sub_f32_e32 v239, v238, v142
	v_cmp_ge_f32_e32 vcc, s76, v239
	v_max_f32_e32 v239, v142, v142
	v_max_f32_e32 v238, v239, v238
	v_sub_f32_e32 v239, v142, v238
	v_mul_f32_e32 v239, 0x3e38aa3b, v239
	v_mfma_f32_32x32x16_bf16 v[32:47], v[204:207], v[220:223], v[32:47]
	ds_read_b64_tr_b16 v[220:221], v180 offset:0x1400
	ds_read_b64_tr_b16 v[222:223], v180 offset:0x1c00
	v_exp_f32_e32 v239, v239
	s_cmp_eq_u64 vcc, exec
	s_cselect_b64 s[14:15], -1, 0
	v_cndmask_b32_e64 v200, v239, 1.0, s[14:15]
	v_cmp_gt_f32_e32 vcc, 1.0, v200
	v_mfma_f32_32x32x16_bf16 v[32:47], v[144:147], v[224:227], v[32:47]
	ds_read_b64_tr_b16 v[224:225], v180 offset:0x2400
	ds_read_b64_tr_b16 v[226:227], v180 offset:0x2c00
	v_cndmask_b32_e64 v241, v238, v142, s[14:15]
	v_mul_f32_e32 v239, 0xbe38aa3b, v241
	v_fmamk_f32 v80, v80, 0x3e38aa3b, v239
	v_fmamk_f32 v81, v81, 0x3e38aa3b, v239
	v_mfma_f32_32x32x16_bf16 v[32:47], v[148:151], v[228:231], v[32:47]
	ds_read_b64_tr_b16 v[228:229], v180 offset:0x3400
	ds_read_b64_tr_b16 v[230:231], v180 offset:0x3c00
	v_fmamk_f32 v82, v82, 0x3e38aa3b, v239
	v_fmamk_f32 v83, v83, 0x3e38aa3b, v239
	v_fmamk_f32 v84, v84, 0x3e38aa3b, v239
	v_fmamk_f32 v85, v85, 0x3e38aa3b, v239
	s_waitcnt lgkmcnt(0)
	v_mfma_f32_32x32x16_bf16 v[16:31], v[138:141], v[216:219], v[16:31]
	ds_read_b64_tr_b16 v[216:217], v180 offset:0x600
	ds_read_b64_tr_b16 v[218:219], v180 offset:0xe00
	v_fmamk_f32 v86, v86, 0x3e38aa3b, v239
	v_fmamk_f32 v87, v87, 0x3e38aa3b, v239
	v_fmamk_f32 v88, v88, 0x3e38aa3b, v239
	v_fmamk_f32 v89, v89, 0x3e38aa3b, v239
	v_mfma_f32_32x32x16_bf16 v[16:31], v[204:207], v[220:223], v[16:31]
	ds_read_b64_tr_b16 v[220:221], v180 offset:0x1600
	ds_read_b64_tr_b16 v[222:223], v180 offset:0x1e00
	v_fmamk_f32 v90, v90, 0x3e38aa3b, v239
	v_fmamk_f32 v91, v91, 0x3e38aa3b, v239
	v_fmamk_f32 v92, v92, 0x3e38aa3b, v239
	v_fmamk_f32 v93, v93, 0x3e38aa3b, v239
	v_mfma_f32_32x32x16_bf16 v[16:31], v[144:147], v[224:227], v[16:31]
	ds_read_b64_tr_b16 v[224:225], v180 offset:0x2600
	ds_read_b64_tr_b16 v[226:227], v180 offset:0x2e00
	v_fmamk_f32 v94, v94, 0x3e38aa3b, v239
	v_fmamk_f32 v95, v95, 0x3e38aa3b, v239
	v_mfma_f32_32x32x16_bf16 v[16:31], v[148:151], v[228:231], v[16:31]
	ds_read_b64_tr_b16 v[228:229], v180 offset:0x3600
	ds_read_b64_tr_b16 v[230:231], v180 offset:0x3e00
	v_exp_f32_e32 v153, v81
	v_exp_f32_e32 v152, v83
	v_exp_f32_e32 v142, v88
	v_exp_f32_e32 v143, v90
	s_waitcnt lgkmcnt(0)
	v_mfma_f32_32x32x16_bf16 v[0:15], v[138:141], v[216:219], v[0:15]
	v_mfma_f32_32x32x16_bf16 v[0:15], v[204:207], v[220:223], v[0:15]
	v_exp_f32_e32 v138, v80
	v_mfma_f32_32x32x16_bf16 v[0:15], v[144:147], v[224:227], v[0:15]
	v_exp_f32_e32 v144, v92
	v_exp_f32_e32 v147, v93
	v_exp_f32_e32 v145, v94
	v_exp_f32_e32 v146, v95
	v_exp_f32_e32 v139, v82
	v_mfma_f32_32x32x16_bf16 v[0:15], v[148:151], v[228:231], v[0:15]
	v_exp_f32_e32 v140, v84
	v_exp_f32_e32 v141, v86
	s_barrier
	s_waitcnt vmcnt(5)
	ds_write_b128 v181, v[114:117]
	s_waitcnt vmcnt(4)
	ds_write_b128 v184, v[118:121]
	s_waitcnt vmcnt(3)
	ds_write_b128 v182, v[122:125] offset:32768
	s_cbranch_vccz .LBB0_175
	s_and_saveexec_b64 s[38:39], s[12:13]
	ds_write_b32 v177, v200 offset:49280
	s_or_b64 exec, exec, s[38:39]
	s_waitcnt lgkmcnt(0)
	v_add_u32_e32 v242, v161, v96
	ds_read_b128 v[244:247], v242 offset:49376
	ds_read_b128 v[148:151], v242 offset:49344
	ds_read_b128 v[204:207], v242 offset:49312
	ds_read_b128 v[216:219], v242 offset:49280
	s_waitcnt lgkmcnt(3)
	v_pk_mul_f32 v[60:61], v[60:61], v[244:245]
	s_waitcnt lgkmcnt(2)
	v_pk_mul_f32 v[56:57], v[56:57], v[148:149]
	s_waitcnt lgkmcnt(1)
	v_pk_mul_f32 v[52:53], v[52:53], v[204:205]
	v_pk_mul_f32 v[62:63], v[62:63], v[246:247]
	v_pk_mul_f32 v[58:59], v[58:59], v[150:151]
	v_pk_mul_f32 v[54:55], v[54:55], v[206:207]
	s_waitcnt lgkmcnt(0)
	v_pk_mul_f32 v[50:51], v[50:51], v[218:219]
	v_pk_mul_f32 v[48:49], v[48:49], v[216:217]
	v_pk_mul_f32 v[44:45], v[44:45], v[244:245]
	v_pk_mul_f32 v[40:41], v[40:41], v[148:149]
	v_pk_mul_f32 v[36:37], v[36:37], v[204:205]
	v_pk_mul_f32 v[46:47], v[46:47], v[246:247]
	v_pk_mul_f32 v[42:43], v[42:43], v[150:151]
	v_pk_mul_f32 v[38:39], v[38:39], v[206:207]
	v_pk_mul_f32 v[34:35], v[34:35], v[218:219]
	v_pk_mul_f32 v[32:33], v[32:33], v[216:217]
	v_pk_mul_f32 v[28:29], v[28:29], v[244:245]
	v_pk_mul_f32 v[24:25], v[24:25], v[148:149]
	v_pk_mul_f32 v[20:21], v[20:21], v[204:205]
	v_pk_mul_f32 v[30:31], v[30:31], v[246:247]
	v_pk_mul_f32 v[26:27], v[26:27], v[150:151]
	v_pk_mul_f32 v[22:23], v[22:23], v[206:207]
	v_pk_mul_f32 v[18:19], v[18:19], v[218:219]
	v_pk_mul_f32 v[16:17], v[16:17], v[216:217]
	v_pk_mul_f32 v[12:13], v[12:13], v[244:245]
	v_pk_mul_f32 v[8:9], v[8:9], v[148:149]
	v_pk_mul_f32 v[4:5], v[4:5], v[204:205]
	v_pk_mul_f32 v[14:15], v[14:15], v[246:247]
	v_pk_mul_f32 v[10:11], v[10:11], v[150:151]
	v_pk_mul_f32 v[6:7], v[6:7], v[206:207]
	v_pk_mul_f32 v[2:3], v[2:3], v[218:219]
	v_pk_mul_f32 v[0:1], v[0:1], v[216:217]
; #define SBAR() __builtin_amdgcn_sched_barrier(0)
; #define SLOAD(i, j) do { const long rb_ = KROW(j); sr_[i].vs0 = *(const bf16x8*)(a.V + (rb_ + sr) * LDV + sc); sr_[i].vs1 = *(const bf16x8*)(a.V + (rb_ + 32 + sr) * LDV + sc); \
;     _Pragma("unroll") for (int c_ = 0; c_ < KCH; ++c_) sr_[i].ks[c_] = *(const bf16x8*)(kptr[c_] + rb_ * kld[c_]); } while (0)
; __device__ __forceinline__ void finishSM(f32x16& p0, f32x16& p1, float alpha, float& l_reg, bf16x8& pa0, bf16x8& pa1, bf16x8& pa2, bf16x8& pa3) {
; #pragma unroll
;     for (int r = 0; r < 16; ++r) p1[r] = __builtin_amdgcn_exp2f(p1[r]);
;     float ps = 0;
; #pragma unroll
;     for (int r = 0; r < 16; ++r) ps += p0[r];
; #pragma unroll
;     for (int r = 0; r < 16; ++r) ps += p1[r];
;     { auto rr = __builtin_amdgcn_permlane32_swap(__float_as_uint(ps), __float_as_uint(ps), false, false);
;       ps = __uint_as_float(rr[0]) + __uint_as_float(rr[1]); }
;     l_reg = l_reg * alpha + ps;
;     ...
;     PK4(p0, 0, pa0); PK4(p0, 8, pa1); PK4(p1, 0, pa2); PK4(p1, 8, pa3);
;     ...
; }
; template <int DQK, int DK1, int LDQ, int LDK, int LDKR, int LDV, int NQL, int SDEPTH>
; __device__ __forceinline__ void attn_core(const AttnArgs& a, char* lds, f32x16 (&o)[4]) {
;     ...
;         SBAR(); QKT(pA0, pA1, K_lds);
;         finishSM(pB0, pB1, alB, l_reg, pa0, pa1, pa2, pa3); SBAR();
;         if (SDEPTH == 1 || j + 3 < NT) SLOAD(SE, j + 1 + SDEPTH); SBAR();
.LBB0_175:
	v_mov_b32_e32 v202, v241
	v_mul_f32_e32 v204, 0xbe38aa3b, v202
	v_exp_f32_e32 v151, v85
	v_exp_f32_e32 v150, v87
	v_exp_f32_e32 v149, v89
	v_exp_f32_e32 v148, v91
	v_fmamk_f32 v222, v64, 0x3e38aa3b, v204
	v_fmamk_f32 v223, v65, 0x3e38aa3b, v204
	v_fmamk_f32 v224, v66, 0x3e38aa3b, v204
	v_fmamk_f32 v225, v67, 0x3e38aa3b, v204
	v_fmamk_f32 v226, v68, 0x3e38aa3b, v204
	v_fmamk_f32 v208, v69, 0x3e38aa3b, v204
	v_fmamk_f32 v216, v70, 0x3e38aa3b, v204
	v_fmamk_f32 v217, v71, 0x3e38aa3b, v204
	v_fmamk_f32 v218, v72, 0x3e38aa3b, v204
	v_fmamk_f32 v219, v73, 0x3e38aa3b, v204
	v_fmamk_f32 v220, v74, 0x3e38aa3b, v204
	v_fmamk_f32 v221, v75, 0x3e38aa3b, v204
	v_fmamk_f32 v206, v76, 0x3e38aa3b, v204
	v_fmamk_f32 v227, v77, 0x3e38aa3b, v204
	v_fmamk_f32 v228, v78, 0x3e38aa3b, v204
	v_fmac_f32_e32 v204, 0x3e38aa3b, v79
	s_waitcnt lgkmcnt(0)
	s_barrier
	ds_read_b128 v[64:67], v186 offset:32768
	ds_read_b128 v[68:71], v186 offset:36864
	v_exp_f32_e32 v205, v223
	v_exp_f32_e32 v223, v204
	v_add_f32_e32 v204, 0, v138
	v_add_f32_e32 v204, v153, v204
	s_waitcnt lgkmcnt(1)
	v_mfma_f32_32x32x16_bf16 v[80:95], v[64:67], v[110:113], 0
	v_add_f32_e32 v204, v139, v204
	v_add_f32_e32 v204, v152, v204
	v_add_f32_e32 v204, v140, v204
	ds_read_b128 v[230:233], v188 offset:32768
	ds_read_b128 v[234:237], v188 offset:36864
	v_add_f32_e32 v204, v151, v204
	v_add_f32_e32 v204, v141, v204
	v_add_f32_e32 v204, v150, v204
	s_waitcnt lgkmcnt(2)
	v_mfma_f32_32x32x16_bf16 v[64:79], v[68:71], v[110:113], 0
	v_add_f32_e32 v204, v142, v204
	v_add_f32_e32 v204, v149, v204
	v_add_f32_e32 v204, v143, v204
	v_add_f32_e32 v204, v148, v204
	v_exp_f32_e32 v191, v222
	v_add_f32_e32 v204, v144, v204
	v_add_f32_e32 v204, v147, v204
	s_waitcnt lgkmcnt(1)
	v_mfma_f32_32x32x16_bf16 v[80:95], v[230:233], v[106:109], v[80:95]
	v_exp_f32_e32 v207, v224
	v_add_f32_e32 v204, v145, v204
	v_exp_f32_e32 v210, v225
	v_add_f32_e32 v204, v146, v204
	v_exp_f32_e32 v211, v226
	v_add_f32_e32 v204, v191, v204
	v_exp_f32_e32 v208, v208
	s_waitcnt lgkmcnt(0)
	v_mfma_f32_32x32x16_bf16 v[64:79], v[234:237], v[106:109], v[64:79]
	ds_read_b128 v[230:233], v190 offset:32768
	ds_read_b128 v[234:237], v190 offset:36864
	v_add_f32_e32 v204, v205, v204
	v_exp_f32_e32 v212, v216
	v_add_f32_e32 v204, v207, v204
	v_exp_f32_e32 v213, v217
	v_add_f32_e32 v204, v210, v204
	v_exp_f32_e32 v216, v218
	s_waitcnt lgkmcnt(1)
	v_mfma_f32_32x32x16_bf16 v[80:95], v[230:233], v[102:105], v[80:95]
	v_add_f32_e32 v204, v211, v204
	v_exp_f32_e32 v217, v219
	v_add_f32_e32 v204, v208, v204
	v_exp_f32_e32 v218, v220
	v_add_f32_e32 v204, v212, v204
	v_exp_f32_e32 v219, v221
	v_add_f32_e32 v204, v213, v204
	s_waitcnt lgkmcnt(0)
	v_mfma_f32_32x32x16_bf16 v[64:79], v[234:237], v[102:105], v[64:79]
	ds_read_b128 v[230:233], v192 offset:32768
	ds_read_b128 v[234:237], v192 offset:36864
	v_exp_f32_e32 v220, v206
	v_add_f32_e32 v204, v216, v204
	v_exp_f32_e32 v221, v227
	v_add_f32_e32 v204, v217, v204
	v_exp_f32_e32 v222, v228
	v_add_f32_e32 v204, v218, v204
	s_waitcnt lgkmcnt(1)
	v_mfma_f32_32x32x16_bf16 v[80:95], v[230:233], v[98:101], v[80:95]
	v_add_f32_e32 v204, v219, v204
	v_add_f32_e32 v204, v220, v204
	v_add_f32_e32 v204, v221, v204
	v_add_f32_e32 v204, v222, v204
	v_add_f32_e32 v204, v223, v204
	v_mov_b32_e32 v206, v204
	v_cvt_pk_bf16_f32 v138, v138, v153
	s_waitcnt lgkmcnt(0)
	v_mfma_f32_32x32x16_bf16 v[64:79], v[234:237], v[98:101], v[64:79]
	ds_read_b64_tr_b16 v[224:225], v179 offset:0x2000
	ds_read_b64_tr_b16 v[226:227], v179 offset:0x2800
	ds_read_b64_tr_b16 v[228:229], v179 offset:0x3000
	ds_read_b64_tr_b16 v[230:231], v179 offset:0x3800
	v_cvt_pk_bf16_f32 v139, v139, v152
	v_cvt_pk_bf16_f32 v140, v140, v151
	v_cvt_pk_bf16_f32 v141, v141, v150
	v_cvt_pk_bf16_f32 v142, v142, v149
	v_cvt_pk_bf16_f32 v143, v143, v148
	v_cvt_pk_bf16_f32 v144, v144, v147
	v_cvt_pk_bf16_f32 v145, v145, v146
	v_cvt_pk_bf16_f32 v146, v191, v205
	v_cvt_pk_bf16_f32 v147, v207, v210
	v_cvt_pk_bf16_f32 v148, v211, v208
	v_cvt_pk_bf16_f32 v149, v212, v213
	v_cvt_pk_bf16_f32 v150, v216, v217
	v_cvt_pk_bf16_f32 v151, v218, v219
	v_cvt_pk_bf16_f32 v152, v220, v221
	v_cvt_pk_bf16_f32 v153, v222, v223
	ds_read_b64_tr_b16 v[216:217], v179 offset:0
	ds_read_b64_tr_b16 v[218:219], v179 offset:0x800
	ds_read_b64_tr_b16 v[220:221], v179 offset:0x1000
	ds_read_b64_tr_b16 v[222:223], v179 offset:0x1800
	v_permlane32_swap_b32_e32 v204, v206
	v_permlane32_swap_b32_e32 v138, v140
	v_permlane32_swap_b32_e32 v139, v141
	v_permlane32_swap_b32_e32 v142, v144
	v_permlane32_swap_b32_e32 v143, v145
	v_permlane32_swap_b32_e32 v146, v148
	v_permlane32_swap_b32_e32 v147, v149
	v_permlane32_swap_b32_e32 v150, v152
	v_permlane32_swap_b32_e32 v151, v153
	s_cmp_gt_u32 s37, 32
	s_cbranch_scc1 .LBB0_177
	s_cmp_lt_u32 s37, 29
	s_cselect_b32 s14, 0, 0xffffffe0
	s_cselect_b32 s15, s18, s86
	s_add_i32 s14, s14, s52
	s_lshl_b32 s14, s14, 6
	s_add_i32 s14, s14, s15
	s_ashr_i32 s15, s14, 31
	v_lshl_add_u64 v[114:115], s[14:15], 0, v[164:165]
	v_lshl_add_u64 v[118:119], v[168:169], 0, s[14:15]
	v_mad_u64_u32 v[116:117], s[38:39], v114, s9, v[170:171]
	v_mad_u64_u32 v[120:121], s[38:39], v118, s9, v[170:171]
	v_mad_i32_i24 v117, v115, s9, v117
	v_mad_i32_i24 v121, v119, s9, v121
	v_mad_i64_i32 v[122:123], s[14:15], s14, v195, v[166:167]
	global_load_dwordx4 v[114:117], v[116:117], off
	s_nop 0
	global_load_dwordx4 v[118:121], v[120:121], off
	s_nop 0
	global_load_dwordx4 v[122:125], v[122:123], off
; #define SBAR() __builtin_amdgcn_sched_barrier(0)
; template <int OFF> __device__ __forceinline__ s16x4 tr_read(int vb) { s16x4 r; asm volatile("ds_read_b64_tr_b16 %0, %1 offset:%2" : "=&v"(r) : "v"(vb), "i"(OFF) : "memory"); return r; }
; template <int D0> __device__ __forceinline__ void pv_one(f32x16& od, int vb, bf16x8 pa0, bf16x8 pa1, bf16x8 pa2, bf16x8 pa3) {
;     const s16x4 l0 = tr_read<v_rd_off(D0, 0, 0)>(vb), h0 = tr_read<v_rd_off(D0, 0, 1)>(vb), l1 = tr_read<v_rd_off(D0, 1, 0)>(vb), h1 = tr_read<v_rd_off(D0, 1, 1)>(vb);
;     const s16x4 l2 = tr_read<v_rd_off(D0, 2, 0)>(vb), h2 = tr_read<v_rd_off(D0, 2, 1)>(vb), l3 = tr_read<v_rd_off(D0, 3, 0)>(vb), h3 = tr_read<v_rd_off(D0, 3, 1)>(vb);
;     asm volatile("s_waitcnt lgkmcnt(0)" ::: "memory"); SBAR();
;     ...
;     od = __builtin_amdgcn_mfma_f32_32x32x16_bf16(pa0, PK(l0, h0), od, 0, 0, 0);
;     od = __builtin_amdgcn_mfma_f32_32x32x16_bf16(pa1, PK(l1, h1), od, 0, 0, 0);
;     od = __builtin_amdgcn_mfma_f32_32x32x16_bf16(pa2, PK(l2, h2), od, 0, 0, 0);
;     od = __builtin_amdgcn_mfma_f32_32x32x16_bf16(pa3, PK(l3, h3), od, 0, 0, 0);
;     ...
; }
; __device__ __forceinline__ void pv_d0(f32x16* o, int vb, bf16x8 pa0, bf16x8 pa1, bf16x8 pa2, bf16x8 pa3) {
;     pv_one<0>(o[0], vb, pa0, pa1, pa2, pa3); pv_one<1>(o[1], vb, pa0, pa1, pa2, pa3); pv_one<2>(o[2], vb, pa0, pa1, pa2, pa3); pv_one<3>(o[3], vb, pa0, pa1, pa2, pa3);
; }
; __device__ __forceinline__ void partialSM(f32x16& p0, f32x16& p1, float& m_reg, float& mn, float& alpha, const float C, const float thr) {
;     float pmax = p0[0];
; #pragma unroll
;     for (int r = 1; r < 16; ++r) pmax = fmaxf(pmax, p0[r]);
; #pragma unroll
;     for (int r = 0; r < 16; ++r) pmax = fmaxf(pmax, p1[r]);
;     { auto rr = __builtin_amdgcn_permlane32_swap(__float_as_uint(pmax), __float_as_uint(pmax), false, false);
;       pmax = fmaxf(__uint_as_float(rr[0]), __uint_as_float(rr[1])); }
;     if (__builtin_expect(__all(pmax - m_reg <= thr), 1)) { mn = m_reg; alpha = 1.f; }
;     else { mn = fmaxf(m_reg, pmax); alpha = __builtin_amdgcn_exp2f((m_reg - mn) * C); m_reg = mn; }
;     const float mnC = -mn * C;
; #pragma unroll
;     for (int r = 0; r < 16; ++r) p0[r] = fmaf(p0[r], C, mnC);
; #pragma unroll
;     for (int r = 0; r < 16; ++r) p1[r] = fmaf(p1[r], C, mnC);
; #pragma unroll
;     for (int r = 0; r < 16; ++r) p0[r] = __builtin_amdgcn_exp2f(p0[r]);
; }
.LBB0_177:
	s_waitcnt lgkmcnt(0)
	s_nop 0
	v_mfma_f32_32x32x16_bf16 v[48:63], v[138:141], v[216:219], v[48:63]
	ds_read_b64_tr_b16 v[216:217], v179 offset:0x200
	ds_read_b64_tr_b16 v[218:219], v179 offset:0xa00
	v_max_f32_e32 v238, v81, v81
	v_max_f32_e32 v239, v80, v80
	v_max_f32_e32 v238, v239, v238
	v_max3_f32 v238, v238, v82, v83
	v_max3_f32 v238, v238, v84, v85
	v_max3_f32 v238, v238, v86, v87
	v_mfma_f32_32x32x16_bf16 v[48:63], v[142:145], v[220:223], v[48:63]
	ds_read_b64_tr_b16 v[220:221], v179 offset:0x1200
	ds_read_b64_tr_b16 v[222:223], v179 offset:0x1a00
	v_max3_f32 v238, v238, v88, v89
	v_max3_f32 v238, v238, v90, v91
	v_max3_f32 v238, v238, v92, v93
	v_max3_f32 v238, v238, v94, v95
	v_max3_f32 v238, v238, v64, v65
	v_max3_f32 v238, v238, v66, v67
	v_mfma_f32_32x32x16_bf16 v[48:63], v[146:149], v[224:227], v[48:63]
	ds_read_b64_tr_b16 v[224:225], v179 offset:0x2200
	ds_read_b64_tr_b16 v[226:227], v179 offset:0x2a00
	v_max3_f32 v238, v238, v68, v69
	v_max3_f32 v238, v238, v70, v71
	v_max3_f32 v238, v238, v72, v73
	v_max3_f32 v238, v238, v74, v75
	v_max3_f32 v238, v238, v76, v77
	v_max3_f32 v238, v238, v78, v79
	v_mfma_f32_32x32x16_bf16 v[48:63], v[150:153], v[228:231], v[48:63]
	ds_read_b64_tr_b16 v[228:229], v179 offset:0x3200
	ds_read_b64_tr_b16 v[230:231], v179 offset:0x3a00
	v_mov_b32_e32 v239, v238
	s_nop 1
	v_permlane32_swap_b32_e32 v238, v239
	v_max_f32_e32 v239, v239, v239
	v_max_f32_e32 v238, v238, v238
	v_max_f32_e32 v238, v238, v239
	s_waitcnt lgkmcnt(0)
	v_mfma_f32_32x32x16_bf16 v[32:47], v[138:141], v[216:219], v[32:47]
	ds_read_b64_tr_b16 v[216:217], v179 offset:0x400
	ds_read_b64_tr_b16 v[218:219], v179 offset:0xc00
	v_sub_f32_e32 v239, v238, v202
	v_cmp_ge_f32_e32 vcc, s76, v239
	v_max_f32_e32 v239, v202, v202
	v_max_f32_e32 v238, v239, v238
	v_sub_f32_e32 v239, v202, v238
	v_mul_f32_e32 v239, 0x3e38aa3b, v239
	v_mfma_f32_32x32x16_bf16 v[32:47], v[142:145], v[220:223], v[32:47]
	ds_read_b64_tr_b16 v[220:221], v179 offset:0x1400
	ds_read_b64_tr_b16 v[222:223], v179 offset:0x1c00
	v_exp_f32_e32 v239, v239
	s_cmp_eq_u64 vcc, exec
	s_cselect_b64 s[14:15], -1, 0
	v_cndmask_b32_e64 v240, v239, 1.0, s[14:15]
	v_cmp_gt_f32_e32 vcc, 1.0, v240
	v_mfma_f32_32x32x16_bf16 v[32:47], v[146:149], v[224:227], v[32:47]
	ds_read_b64_tr_b16 v[224:225], v179 offset:0x2400
	ds_read_b64_tr_b16 v[226:227], v179 offset:0x2c00
	v_cndmask_b32_e64 v241, v238, v202, s[14:15]
	v_mul_f32_e32 v239, 0xbe38aa3b, v241
	v_fmamk_f32 v80, v80, 0x3e38aa3b, v239
	v_fmamk_f32 v81, v81, 0x3e38aa3b, v239
	v_mfma_f32_32x32x16_bf16 v[32:47], v[150:153], v[228:231], v[32:47]
	ds_read_b64_tr_b16 v[228:229], v179 offset:0x3400
	ds_read_b64_tr_b16 v[230:231], v179 offset:0x3c00
	v_fmamk_f32 v82, v82, 0x3e38aa3b, v239
	v_fmamk_f32 v83, v83, 0x3e38aa3b, v239
	v_fmamk_f32 v84, v84, 0x3e38aa3b, v239
	v_fmamk_f32 v85, v85, 0x3e38aa3b, v239
	s_waitcnt lgkmcnt(0)
	v_mfma_f32_32x32x16_bf16 v[16:31], v[138:141], v[216:219], v[16:31]
	ds_read_b64_tr_b16 v[216:217], v179 offset:0x600
	ds_read_b64_tr_b16 v[218:219], v179 offset:0xe00
	v_fmamk_f32 v86, v86, 0x3e38aa3b, v239
	v_fmamk_f32 v87, v87, 0x3e38aa3b, v239
	v_fmamk_f32 v88, v88, 0x3e38aa3b, v239
	v_fmamk_f32 v89, v89, 0x3e38aa3b, v239
	v_mfma_f32_32x32x16_bf16 v[16:31], v[142:145], v[220:223], v[16:31]
	ds_read_b64_tr_b16 v[220:221], v179 offset:0x1600
	ds_read_b64_tr_b16 v[222:223], v179 offset:0x1e00
	v_fmamk_f32 v90, v90, 0x3e38aa3b, v239
	v_fmamk_f32 v91, v91, 0x3e38aa3b, v239
	v_fmamk_f32 v92, v92, 0x3e38aa3b, v239
	v_fmamk_f32 v93, v93, 0x3e38aa3b, v239
	v_mfma_f32_32x32x16_bf16 v[16:31], v[146:149], v[224:227], v[16:31]
	ds_read_b64_tr_b16 v[224:225], v179 offset:0x2600
	ds_read_b64_tr_b16 v[226:227], v179 offset:0x2e00
	v_fmamk_f32 v94, v94, 0x3e38aa3b, v239
	v_mfma_f32_32x32x16_bf16 v[16:31], v[150:153], v[228:231], v[16:31]
	ds_read_b64_tr_b16 v[228:229], v179 offset:0x3600
	ds_read_b64_tr_b16 v[230:231], v179 offset:0x3e00
	v_exp_f32_e32 v208, v82
	v_exp_f32_e32 v202, v87
	s_waitcnt lgkmcnt(0)
	v_mfma_f32_32x32x16_bf16 v[0:15], v[138:141], v[216:219], v[0:15]
	v_mfma_f32_32x32x16_bf16 v[0:15], v[142:145], v[220:223], v[0:15]
	v_exp_f32_e32 v145, v92
	v_exp_f32_e32 v144, v94
	v_exp_f32_e32 v217, v80
	v_mfma_f32_32x32x16_bf16 v[0:15], v[146:149], v[224:227], v[0:15]
	v_exp_f32_e32 v149, v88
	v_exp_f32_e32 v147, v90
	v_exp_f32_e32 v148, v93
	v_exp_f32_e32 v219, v81
	v_mfma_f32_32x32x16_bf16 v[0:15], v[150:153], v[228:231], v[0:15]
	v_exp_f32_e32 v218, v83
	v_exp_f32_e32 v216, v85
	v_mov_b32_e32 v143, v240
	s_barrier
	s_waitcnt vmcnt(2)
	ds_write_b128 v181, v[126:129] offset:16384
	s_waitcnt vmcnt(1)
	ds_write_b128 v184, v[130:133] offset:16384
	s_waitcnt vmcnt(0)
	ds_write_b128 v182, v[134:137] offset:40960
	s_cbranch_vccz .LBB0_181
	s_and_saveexec_b64 s[38:39], s[12:13]
	ds_write_b32 v177, v143 offset:49280
	s_or_b64 exec, exec, s[38:39]
	s_waitcnt lgkmcnt(0)
	v_add_u32_e32 v139, v161, v96
	ds_read_b128 v[126:129], v139 offset:49376
	ds_read_b128 v[130:133], v139 offset:49344
	ds_read_b128 v[134:137], v139 offset:49312
	ds_read_b128 v[244:247], v139 offset:49280
	s_waitcnt lgkmcnt(3)
	v_pk_mul_f32 v[60:61], v[60:61], v[126:127]
	s_waitcnt lgkmcnt(2)
	v_pk_mul_f32 v[56:57], v[56:57], v[130:131]
	s_waitcnt lgkmcnt(1)
	v_pk_mul_f32 v[52:53], v[52:53], v[134:135]
	v_pk_mul_f32 v[62:63], v[62:63], v[128:129]
	v_pk_mul_f32 v[58:59], v[58:59], v[132:133]
	v_pk_mul_f32 v[54:55], v[54:55], v[136:137]
	s_waitcnt lgkmcnt(0)
	v_pk_mul_f32 v[50:51], v[50:51], v[246:247]
	v_pk_mul_f32 v[48:49], v[48:49], v[244:245]
	v_pk_mul_f32 v[44:45], v[44:45], v[126:127]
	v_pk_mul_f32 v[40:41], v[40:41], v[130:131]
	v_pk_mul_f32 v[36:37], v[36:37], v[134:135]
	v_pk_mul_f32 v[46:47], v[46:47], v[128:129]
	v_pk_mul_f32 v[42:43], v[42:43], v[132:133]
	v_pk_mul_f32 v[38:39], v[38:39], v[136:137]
	v_pk_mul_f32 v[34:35], v[34:35], v[246:247]
	v_pk_mul_f32 v[32:33], v[32:33], v[244:245]
	v_pk_mul_f32 v[28:29], v[28:29], v[126:127]
	v_pk_mul_f32 v[24:25], v[24:25], v[130:131]
	v_pk_mul_f32 v[20:21], v[20:21], v[134:135]
	v_pk_mul_f32 v[30:31], v[30:31], v[128:129]
	v_pk_mul_f32 v[26:27], v[26:27], v[132:133]
	v_pk_mul_f32 v[22:23], v[22:23], v[136:137]
	v_pk_mul_f32 v[18:19], v[18:19], v[246:247]
	v_pk_mul_f32 v[16:17], v[16:17], v[244:245]
	v_pk_mul_f32 v[12:13], v[12:13], v[126:127]
	v_pk_mul_f32 v[8:9], v[8:9], v[130:131]
	v_pk_mul_f32 v[4:5], v[4:5], v[134:135]
	v_pk_mul_f32 v[14:15], v[14:15], v[128:129]
	v_pk_mul_f32 v[10:11], v[10:11], v[132:133]
	v_pk_mul_f32 v[6:7], v[6:7], v[136:137]
	v_pk_mul_f32 v[2:3], v[2:3], v[246:247]
	v_pk_mul_f32 v[0:1], v[0:1], v[244:245]
